# v27 plus: the fused post-norm epilogue's per-row sum-of-squares reductions are batched (8 cross-lane exchanges in flight, two waits instead of sixteen) in the K=2816 and S5-out fused GEMMs
# speedup vs baseline: 1.0143x; 1.0022x over previous
.LBB0_477:
	s_lshl_b32 s26, s21, 8
	s_lshl_b32 s10, s20, 8
	v_or_b32_e32 v194, s10, v212
	v_add_u32_e32 v198, s26, v210
	v_ashrrev_i32_e32 v195, 31, v194
	v_ashrrev_i32_e32 v199, 31, v198
	v_lshl_add_u64 v[192:193], v[194:195], 1, s[44:45]
	v_lshlrev_b64 v[112:113], 11, v[198:199]
	v_lshl_add_u64 v[112:113], v[192:193], 0, v[112:113]
	flat_load_dwordx4 v[172:175], v[112:113]
	flat_load_dwordx4 v[168:171], v[112:113] offset:256
	v_or_b32_e32 v112, 16, v198
	v_ashrrev_i32_e32 v113, 31, v112
	v_lshlrev_b64 v[112:113], 11, v[112:113]
	v_lshl_add_u64 v[112:113], v[192:193], 0, v[112:113]
	flat_load_dwordx4 v[164:167], v[112:113]
	flat_load_dwordx4 v[160:163], v[112:113] offset:256
	v_or_b32_e32 v112, 32, v198
	v_ashrrev_i32_e32 v113, 31, v112
	v_lshlrev_b64 v[112:113], 11, v[112:113]
	v_lshl_add_u64 v[112:113], v[192:193], 0, v[112:113]
	flat_load_dwordx4 v[156:159], v[112:113]
	flat_load_dwordx4 v[152:155], v[112:113] offset:256
	v_or_b32_e32 v112, 48, v198
	v_ashrrev_i32_e32 v113, 31, v112
	v_lshlrev_b64 v[112:113], 11, v[112:113]
	v_lshl_add_u64 v[112:113], v[192:193], 0, v[112:113]
	flat_load_dwordx4 v[148:151], v[112:113]
	flat_load_dwordx4 v[144:147], v[112:113] offset:256
	v_and_b32_e32 v113, 64, v204
	v_xor_b32_e32 v112, 16, v204
	v_add_u32_e32 v113, 64, v113
	v_cmp_lt_i32_e32 vcc, v112, v113
	v_cndmask_b32_e32 v112, v204, v112, vcc
	v_lshlrev_b32_e32 v236, 2, v112
	v_xor_b32_e32 v115, 32, v204
	v_cmp_lt_i32_e32 vcc, v115, v113
	v_cndmask_b32_e32 v113, v204, v115, vcc
	v_lshlrev_b32_e32 v237, 2, v113
	v_mul_f32_e32 v240, v141, v141
	v_mul_f32_e32 v114, v143, v143
	v_fmac_f32_e32 v240, v140, v140
	v_fmac_f32_e32 v114, v142, v142
	v_add_f32_e32 v240, v240, v114
	v_mul_f32_e32 v113, v137, v137
	v_mul_f32_e32 v114, v139, v139
	v_fmac_f32_e32 v113, v136, v136
	v_fmac_f32_e32 v114, v138, v138
	v_add_f32_e32 v113, v113, v114
	v_add_f32_e32 v240, v240, v113
	v_mul_f32_e32 v113, v133, v133
	v_mul_f32_e32 v114, v135, v135
	v_fmac_f32_e32 v113, v132, v132
	v_fmac_f32_e32 v114, v134, v134
	v_add_f32_e32 v113, v113, v114
	v_add_f32_e32 v240, v240, v113
	v_mul_f32_e32 v113, v121, v121
	v_mul_f32_e32 v114, v123, v123
	v_fmac_f32_e32 v113, v120, v120
	v_fmac_f32_e32 v114, v122, v122
	v_add_f32_e32 v113, v113, v114
	v_add_f32_e32 v240, v240, v113
	v_mul_f32_e32 v241, v109, v109
	v_mul_f32_e32 v114, v111, v111
	v_fmac_f32_e32 v241, v108, v108
	v_fmac_f32_e32 v114, v110, v110
	v_add_f32_e32 v241, v241, v114
	v_mul_f32_e32 v113, v105, v105
	v_mul_f32_e32 v114, v107, v107
	v_fmac_f32_e32 v113, v104, v104
	v_fmac_f32_e32 v114, v106, v106
	v_add_f32_e32 v113, v113, v114
	v_add_f32_e32 v241, v241, v113
	v_mul_f32_e32 v113, v101, v101
	v_mul_f32_e32 v114, v103, v103
	v_fmac_f32_e32 v113, v100, v100
	v_fmac_f32_e32 v114, v102, v102
	v_add_f32_e32 v113, v113, v114
	v_add_f32_e32 v241, v241, v113
	v_mul_f32_e32 v113, v97, v97
	v_mul_f32_e32 v114, v99, v99
	v_fmac_f32_e32 v113, v96, v96
	v_fmac_f32_e32 v114, v98, v98
	v_add_f32_e32 v113, v113, v114
	v_add_f32_e32 v241, v241, v113
	v_mul_f32_e32 v242, v93, v93
	v_mul_f32_e32 v114, v95, v95
	v_fmac_f32_e32 v242, v92, v92
	v_fmac_f32_e32 v114, v94, v94
	v_add_f32_e32 v242, v242, v114
	v_mul_f32_e32 v113, v89, v89
	v_mul_f32_e32 v114, v91, v91
	v_fmac_f32_e32 v113, v88, v88
	v_fmac_f32_e32 v114, v90, v90
	v_add_f32_e32 v113, v113, v114
	v_add_f32_e32 v242, v242, v113
	v_mul_f32_e32 v113, v85, v85
	v_mul_f32_e32 v114, v87, v87
	v_fmac_f32_e32 v113, v84, v84
	v_fmac_f32_e32 v114, v86, v86
	v_add_f32_e32 v113, v113, v114
	v_add_f32_e32 v242, v242, v113
	v_mul_f32_e32 v113, v81, v81
	v_mul_f32_e32 v114, v83, v83
	v_fmac_f32_e32 v113, v80, v80
	v_fmac_f32_e32 v114, v82, v82
	v_add_f32_e32 v113, v113, v114
	v_add_f32_e32 v242, v242, v113
	v_mul_f32_e32 v243, v77, v77
	v_mul_f32_e32 v114, v79, v79
	v_fmac_f32_e32 v243, v76, v76
	v_fmac_f32_e32 v114, v78, v78
	v_add_f32_e32 v243, v243, v114
	v_mul_f32_e32 v113, v73, v73
	v_mul_f32_e32 v114, v75, v75
	v_fmac_f32_e32 v113, v72, v72
	v_fmac_f32_e32 v114, v74, v74
	v_add_f32_e32 v113, v113, v114
	v_add_f32_e32 v243, v243, v113
	v_mul_f32_e32 v113, v69, v69
	v_mul_f32_e32 v114, v71, v71
	v_fmac_f32_e32 v113, v68, v68
	v_fmac_f32_e32 v114, v70, v70
	v_add_f32_e32 v113, v113, v114
	v_add_f32_e32 v243, v243, v113
	v_mul_f32_e32 v113, v65, v65
	v_mul_f32_e32 v114, v67, v67
	v_fmac_f32_e32 v113, v64, v64
	v_fmac_f32_e32 v114, v66, v66
	v_add_f32_e32 v113, v113, v114
	v_add_f32_e32 v243, v243, v113
	v_mul_f32_e32 v244, v61, v61
	v_mul_f32_e32 v114, v63, v63
	v_fmac_f32_e32 v244, v60, v60
	v_fmac_f32_e32 v114, v62, v62
	v_add_f32_e32 v244, v244, v114
	v_mul_f32_e32 v113, v57, v57
	v_mul_f32_e32 v114, v59, v59
	v_fmac_f32_e32 v113, v56, v56
	v_fmac_f32_e32 v114, v58, v58
	v_add_f32_e32 v113, v113, v114
	v_add_f32_e32 v244, v244, v113
	v_mul_f32_e32 v113, v53, v53
	v_mul_f32_e32 v114, v55, v55
	v_fmac_f32_e32 v113, v52, v52
	v_fmac_f32_e32 v114, v54, v54
	v_add_f32_e32 v113, v113, v114
	v_add_f32_e32 v244, v244, v113
	v_mul_f32_e32 v113, v49, v49
	v_mul_f32_e32 v114, v51, v51
	v_fmac_f32_e32 v113, v48, v48
	v_fmac_f32_e32 v114, v50, v50
	v_add_f32_e32 v113, v113, v114
	v_add_f32_e32 v244, v244, v113
	v_mul_f32_e32 v245, v45, v45
	v_mul_f32_e32 v114, v47, v47
	v_fmac_f32_e32 v245, v44, v44
	v_fmac_f32_e32 v114, v46, v46
	v_add_f32_e32 v245, v245, v114
	v_mul_f32_e32 v113, v41, v41
	v_mul_f32_e32 v114, v43, v43
	v_fmac_f32_e32 v113, v40, v40
	v_fmac_f32_e32 v114, v42, v42
	v_add_f32_e32 v113, v113, v114
	v_add_f32_e32 v245, v245, v113
	v_mul_f32_e32 v113, v37, v37
	v_mul_f32_e32 v114, v39, v39
	v_fmac_f32_e32 v113, v36, v36
	v_fmac_f32_e32 v114, v38, v38
	v_add_f32_e32 v113, v113, v114
	v_add_f32_e32 v245, v245, v113
	v_mul_f32_e32 v113, v33, v33
	v_mul_f32_e32 v114, v35, v35
	v_fmac_f32_e32 v113, v32, v32
	v_fmac_f32_e32 v114, v34, v34
	v_add_f32_e32 v113, v113, v114
	v_add_f32_e32 v245, v245, v113
	v_mul_f32_e32 v246, v29, v29
	v_mul_f32_e32 v114, v31, v31
	v_fmac_f32_e32 v246, v28, v28
	v_fmac_f32_e32 v114, v30, v30
	v_add_f32_e32 v246, v246, v114
	v_mul_f32_e32 v113, v25, v25
	v_mul_f32_e32 v114, v27, v27
	v_fmac_f32_e32 v113, v24, v24
	v_fmac_f32_e32 v114, v26, v26
	v_add_f32_e32 v113, v113, v114
	v_add_f32_e32 v246, v246, v113
	v_mul_f32_e32 v113, v21, v21
	v_mul_f32_e32 v114, v23, v23
	v_fmac_f32_e32 v113, v20, v20
	v_fmac_f32_e32 v114, v22, v22
	v_add_f32_e32 v113, v113, v114
	v_add_f32_e32 v246, v246, v113
	v_mul_f32_e32 v113, v17, v17
	v_mul_f32_e32 v114, v19, v19
	v_fmac_f32_e32 v113, v16, v16
	v_fmac_f32_e32 v114, v18, v18
	v_add_f32_e32 v113, v113, v114
	v_add_f32_e32 v246, v246, v113
	v_mul_f32_e32 v247, v13, v13
	v_mul_f32_e32 v114, v15, v15
	v_fmac_f32_e32 v247, v12, v12
	v_fmac_f32_e32 v114, v14, v14
	v_add_f32_e32 v247, v247, v114
	v_mul_f32_e32 v113, v9, v9
	v_mul_f32_e32 v114, v11, v11
	v_fmac_f32_e32 v113, v8, v8
	v_fmac_f32_e32 v114, v10, v10
	v_add_f32_e32 v113, v113, v114
	v_add_f32_e32 v247, v247, v113
	v_mul_f32_e32 v113, v5, v5
	v_mul_f32_e32 v114, v7, v7
	v_fmac_f32_e32 v113, v4, v4
	v_fmac_f32_e32 v114, v6, v6
	v_add_f32_e32 v113, v113, v114
	v_add_f32_e32 v247, v247, v113
	v_mul_f32_e32 v113, v1, v1
	v_mul_f32_e32 v114, v3, v3
	v_fmac_f32_e32 v113, v0, v0
	v_fmac_f32_e32 v114, v2, v2
	v_add_f32_e32 v113, v113, v114
	v_add_f32_e32 v247, v247, v113
	ds_bpermute_b32 v248, v236, v240
	ds_bpermute_b32 v249, v236, v241
	ds_bpermute_b32 v250, v236, v242
	ds_bpermute_b32 v251, v236, v243
	ds_bpermute_b32 v116, v236, v244
	ds_bpermute_b32 v117, v236, v245
	ds_bpermute_b32 v118, v236, v246
	ds_bpermute_b32 v119, v236, v247
	s_waitcnt lgkmcnt(0)
	v_add_f32_e32 v240, v240, v248
	v_add_f32_e32 v241, v241, v249
	v_add_f32_e32 v242, v242, v250
	v_add_f32_e32 v243, v243, v251
	v_add_f32_e32 v244, v244, v116
	v_add_f32_e32 v245, v245, v117
	v_add_f32_e32 v246, v246, v118
	v_add_f32_e32 v247, v247, v119
	ds_bpermute_b32 v248, v237, v240
	ds_bpermute_b32 v249, v237, v241
	ds_bpermute_b32 v250, v237, v242
	ds_bpermute_b32 v251, v237, v243
	ds_bpermute_b32 v116, v237, v244
	ds_bpermute_b32 v117, v237, v245
	ds_bpermute_b32 v118, v237, v246
	ds_bpermute_b32 v119, v237, v247
	s_waitcnt lgkmcnt(0)
	s_and_saveexec_b64 s[0:1], s[2:3]
	v_add_f32_e32 v240, v240, v248
	ds_write_b32 v234, v240
	v_add_f32_e32 v241, v241, v249
	ds_write_b32 v234, v241 offset:256
	v_add_f32_e32 v242, v242, v250
	ds_write_b32 v234, v242 offset:512
	v_add_f32_e32 v243, v243, v251
	ds_write_b32 v234, v243 offset:768
	v_add_f32_e32 v244, v244, v116
	ds_write_b32 v234, v244 offset:2048
	v_add_f32_e32 v245, v245, v117
	ds_write_b32 v234, v245 offset:2304
	v_add_f32_e32 v246, v246, v118
	ds_write_b32 v234, v246 offset:2560
	v_add_f32_e32 v247, v247, v119
	ds_write_b32 v234, v247 offset:2816
	s_or_b64 exec, exec, s[0:1]
	v_add_u32_e32 v114, s26, v213
	s_waitcnt lgkmcnt(0)
	s_barrier
	v_ashrrev_i32_e32 v115, 31, v114
	s_waitcnt lgkmcnt(0)
	v_lshlrev_b64 v[112:113], 5, v[114:115]
	v_lshl_add_u64 v[112:113], s[76:77], 0, v[112:113]
	v_add_u32_e32 v238, 0x20400, v235
	s_and_saveexec_b64 s[0:1], s[4:5]
	s_cbranch_execz .LBB0_495
	ds_read_b128 v[116:119], v238
	s_ashr_i32 s21, s20, 31
	s_waitcnt lgkmcnt(0)
	v_mov_b32_e32 v124, v117
	v_mov_b32_e32 v125, v118
	v_mov_b32_e32 v117, v119
	v_pk_add_f32 v[116:117], v[124:125], v[116:117]
	v_lshl_add_u64 v[118:119], s[20:21], 3, v[112:113]
	v_pk_add_f32 v[116:117], v[116:117], v[116:117] op_sel:[0,1] op_sel_hi:[1,0]
	s_nop 0
	v_mov_b32_e32 v117, s84
	s_waitcnt vmcnt(0)
	flat_store_dwordx2 v[118:119], v[116:117] sc1

.LBB0_602:
	s_lshl_b32 s21, s19, 8
	s_lshl_b32 s10, s18, 8
	v_or_b32_e32 v194, s10, v212
	v_add_u32_e32 v198, s21, v210
	v_ashrrev_i32_e32 v195, 31, v194
	v_ashrrev_i32_e32 v199, 31, v198
	v_lshl_add_u64 v[192:193], v[194:195], 1, s[44:45]
	v_lshlrev_b64 v[112:113], 11, v[198:199]
	v_lshl_add_u64 v[112:113], v[192:193], 0, v[112:113]
	flat_load_dwordx4 v[172:175], v[112:113]
	flat_load_dwordx4 v[168:171], v[112:113] offset:256
	v_or_b32_e32 v112, 16, v198
	v_ashrrev_i32_e32 v113, 31, v112
	v_lshlrev_b64 v[112:113], 11, v[112:113]
	v_lshl_add_u64 v[112:113], v[192:193], 0, v[112:113]
	flat_load_dwordx4 v[164:167], v[112:113]
	flat_load_dwordx4 v[160:163], v[112:113] offset:256
	v_or_b32_e32 v112, 32, v198
	v_ashrrev_i32_e32 v113, 31, v112
	v_lshlrev_b64 v[112:113], 11, v[112:113]
	v_lshl_add_u64 v[112:113], v[192:193], 0, v[112:113]
	flat_load_dwordx4 v[156:159], v[112:113]
	flat_load_dwordx4 v[152:155], v[112:113] offset:256
	v_or_b32_e32 v112, 48, v198
	v_ashrrev_i32_e32 v113, 31, v112
	v_lshlrev_b64 v[112:113], 11, v[112:113]
	v_lshl_add_u64 v[112:113], v[192:193], 0, v[112:113]
	flat_load_dwordx4 v[148:151], v[112:113]
	flat_load_dwordx4 v[144:147], v[112:113] offset:256
	v_and_b32_e32 v113, 64, v204
	v_xor_b32_e32 v112, 16, v204
	v_add_u32_e32 v113, 64, v113
	v_cmp_lt_i32_e32 vcc, v112, v113
	v_cndmask_b32_e32 v112, v204, v112, vcc
	v_lshlrev_b32_e32 v236, 2, v112
	v_xor_b32_e32 v115, 32, v204
	v_cmp_lt_i32_e32 vcc, v115, v113
	v_cndmask_b32_e32 v113, v204, v115, vcc
	v_lshlrev_b32_e32 v237, 2, v113
	v_mul_f32_e32 v240, v141, v141
	v_mul_f32_e32 v114, v143, v143
	v_fmac_f32_e32 v240, v140, v140
	v_fmac_f32_e32 v114, v142, v142
	v_add_f32_e32 v240, v240, v114
	v_mul_f32_e32 v113, v137, v137
	v_mul_f32_e32 v114, v139, v139
	v_fmac_f32_e32 v113, v136, v136
	v_fmac_f32_e32 v114, v138, v138
	v_add_f32_e32 v113, v113, v114
	v_add_f32_e32 v240, v240, v113
	v_mul_f32_e32 v113, v133, v133
	v_mul_f32_e32 v114, v135, v135
	v_fmac_f32_e32 v113, v132, v132
	v_fmac_f32_e32 v114, v134, v134
	v_add_f32_e32 v113, v113, v114
	v_add_f32_e32 v240, v240, v113
	v_mul_f32_e32 v113, v121, v121
	v_mul_f32_e32 v114, v123, v123
	v_fmac_f32_e32 v113, v120, v120
	v_fmac_f32_e32 v114, v122, v122
	v_add_f32_e32 v113, v113, v114
	v_add_f32_e32 v240, v240, v113
	v_mul_f32_e32 v241, v109, v109
	v_mul_f32_e32 v114, v111, v111
	v_fmac_f32_e32 v241, v108, v108
	v_fmac_f32_e32 v114, v110, v110
	v_add_f32_e32 v241, v241, v114
	v_mul_f32_e32 v113, v105, v105
	v_mul_f32_e32 v114, v107, v107
	v_fmac_f32_e32 v113, v104, v104
	v_fmac_f32_e32 v114, v106, v106
	v_add_f32_e32 v113, v113, v114
	v_add_f32_e32 v241, v241, v113
	v_mul_f32_e32 v113, v101, v101
	v_mul_f32_e32 v114, v103, v103
	v_fmac_f32_e32 v113, v100, v100
	v_fmac_f32_e32 v114, v102, v102
	v_add_f32_e32 v113, v113, v114
	v_add_f32_e32 v241, v241, v113
	v_mul_f32_e32 v113, v97, v97
	v_mul_f32_e32 v114, v99, v99
	v_fmac_f32_e32 v113, v96, v96
	v_fmac_f32_e32 v114, v98, v98
	v_add_f32_e32 v113, v113, v114
	v_add_f32_e32 v241, v241, v113
	v_mul_f32_e32 v242, v93, v93
	v_mul_f32_e32 v114, v95, v95
	v_fmac_f32_e32 v242, v92, v92
	v_fmac_f32_e32 v114, v94, v94
	v_add_f32_e32 v242, v242, v114
	v_mul_f32_e32 v113, v89, v89
	v_mul_f32_e32 v114, v91, v91
	v_fmac_f32_e32 v113, v88, v88
	v_fmac_f32_e32 v114, v90, v90
	v_add_f32_e32 v113, v113, v114
	v_add_f32_e32 v242, v242, v113
	v_mul_f32_e32 v113, v85, v85
	v_mul_f32_e32 v114, v87, v87
	v_fmac_f32_e32 v113, v84, v84
	v_fmac_f32_e32 v114, v86, v86
	v_add_f32_e32 v113, v113, v114
	v_add_f32_e32 v242, v242, v113
	v_mul_f32_e32 v113, v81, v81
	v_mul_f32_e32 v114, v83, v83
	v_fmac_f32_e32 v113, v80, v80
	v_fmac_f32_e32 v114, v82, v82
	v_add_f32_e32 v113, v113, v114
	v_add_f32_e32 v242, v242, v113
	v_mul_f32_e32 v243, v77, v77
	v_mul_f32_e32 v114, v79, v79
	v_fmac_f32_e32 v243, v76, v76
	v_fmac_f32_e32 v114, v78, v78
	v_add_f32_e32 v243, v243, v114
	v_mul_f32_e32 v113, v73, v73
	v_mul_f32_e32 v114, v75, v75
	v_fmac_f32_e32 v113, v72, v72
	v_fmac_f32_e32 v114, v74, v74
	v_add_f32_e32 v113, v113, v114
	v_add_f32_e32 v243, v243, v113
	v_mul_f32_e32 v113, v69, v69
	v_mul_f32_e32 v114, v71, v71
	v_fmac_f32_e32 v113, v68, v68
	v_fmac_f32_e32 v114, v70, v70
	v_add_f32_e32 v113, v113, v114
	v_add_f32_e32 v243, v243, v113
	v_mul_f32_e32 v113, v65, v65
	v_mul_f32_e32 v114, v67, v67
	v_fmac_f32_e32 v113, v64, v64
	v_fmac_f32_e32 v114, v66, v66
	v_add_f32_e32 v113, v113, v114
	v_add_f32_e32 v243, v243, v113
	v_mul_f32_e32 v244, v61, v61
	v_mul_f32_e32 v114, v63, v63
	v_fmac_f32_e32 v244, v60, v60
	v_fmac_f32_e32 v114, v62, v62
	v_add_f32_e32 v244, v244, v114
	v_mul_f32_e32 v113, v57, v57
	v_mul_f32_e32 v114, v59, v59
	v_fmac_f32_e32 v113, v56, v56
	v_fmac_f32_e32 v114, v58, v58
	v_add_f32_e32 v113, v113, v114
	v_add_f32_e32 v244, v244, v113
	v_mul_f32_e32 v113, v53, v53
	v_mul_f32_e32 v114, v55, v55
	v_fmac_f32_e32 v113, v52, v52
	v_fmac_f32_e32 v114, v54, v54
	v_add_f32_e32 v113, v113, v114
	v_add_f32_e32 v244, v244, v113
	v_mul_f32_e32 v113, v49, v49
	v_mul_f32_e32 v114, v51, v51
	v_fmac_f32_e32 v113, v48, v48
	v_fmac_f32_e32 v114, v50, v50
	v_add_f32_e32 v113, v113, v114
	v_add_f32_e32 v244, v244, v113
	v_mul_f32_e32 v245, v45, v45
	v_mul_f32_e32 v114, v47, v47
	v_fmac_f32_e32 v245, v44, v44
	v_fmac_f32_e32 v114, v46, v46
	v_add_f32_e32 v245, v245, v114
	v_mul_f32_e32 v113, v41, v41
	v_mul_f32_e32 v114, v43, v43
	v_fmac_f32_e32 v113, v40, v40
	v_fmac_f32_e32 v114, v42, v42
	v_add_f32_e32 v113, v113, v114
	v_add_f32_e32 v245, v245, v113
	v_mul_f32_e32 v113, v37, v37
	v_mul_f32_e32 v114, v39, v39
	v_fmac_f32_e32 v113, v36, v36
	v_fmac_f32_e32 v114, v38, v38
	v_add_f32_e32 v113, v113, v114
	v_add_f32_e32 v245, v245, v113
	v_mul_f32_e32 v113, v33, v33
	v_mul_f32_e32 v114, v35, v35
	v_fmac_f32_e32 v113, v32, v32
	v_fmac_f32_e32 v114, v34, v34
	v_add_f32_e32 v113, v113, v114
	v_add_f32_e32 v245, v245, v113
	v_mul_f32_e32 v246, v29, v29
	v_mul_f32_e32 v114, v31, v31
	v_fmac_f32_e32 v246, v28, v28
	v_fmac_f32_e32 v114, v30, v30
	v_add_f32_e32 v246, v246, v114
	v_mul_f32_e32 v113, v25, v25
	v_mul_f32_e32 v114, v27, v27
	v_fmac_f32_e32 v113, v24, v24
	v_fmac_f32_e32 v114, v26, v26
	v_add_f32_e32 v113, v113, v114
	v_add_f32_e32 v246, v246, v113
	v_mul_f32_e32 v113, v21, v21
	v_mul_f32_e32 v114, v23, v23
	v_fmac_f32_e32 v113, v20, v20
	v_fmac_f32_e32 v114, v22, v22
	v_add_f32_e32 v113, v113, v114
	v_add_f32_e32 v246, v246, v113
	v_mul_f32_e32 v113, v17, v17
	v_mul_f32_e32 v114, v19, v19
	v_fmac_f32_e32 v113, v16, v16
	v_fmac_f32_e32 v114, v18, v18
	v_add_f32_e32 v113, v113, v114
	v_add_f32_e32 v246, v246, v113
	v_mul_f32_e32 v247, v13, v13
	v_mul_f32_e32 v114, v15, v15
	v_fmac_f32_e32 v247, v12, v12
	v_fmac_f32_e32 v114, v14, v14
	v_add_f32_e32 v247, v247, v114
	v_mul_f32_e32 v113, v9, v9
	v_mul_f32_e32 v114, v11, v11
	v_fmac_f32_e32 v113, v8, v8
	v_fmac_f32_e32 v114, v10, v10
	v_add_f32_e32 v113, v113, v114
	v_add_f32_e32 v247, v247, v113
	v_mul_f32_e32 v113, v5, v5
	v_mul_f32_e32 v114, v7, v7
	v_fmac_f32_e32 v113, v4, v4
	v_fmac_f32_e32 v114, v6, v6
	v_add_f32_e32 v113, v113, v114
	v_add_f32_e32 v247, v247, v113
	v_mul_f32_e32 v113, v1, v1
	v_mul_f32_e32 v114, v3, v3
	v_fmac_f32_e32 v113, v0, v0
	v_fmac_f32_e32 v114, v2, v2
	v_add_f32_e32 v113, v113, v114
	v_add_f32_e32 v247, v247, v113
	ds_bpermute_b32 v248, v236, v240
	ds_bpermute_b32 v249, v236, v241
	ds_bpermute_b32 v250, v236, v242
	ds_bpermute_b32 v251, v236, v243
	ds_bpermute_b32 v116, v236, v244
	ds_bpermute_b32 v117, v236, v245
	ds_bpermute_b32 v118, v236, v246
	ds_bpermute_b32 v119, v236, v247
	s_waitcnt lgkmcnt(0)
	v_add_f32_e32 v240, v240, v248
	v_add_f32_e32 v241, v241, v249
	v_add_f32_e32 v242, v242, v250
	v_add_f32_e32 v243, v243, v251
	v_add_f32_e32 v244, v244, v116
	v_add_f32_e32 v245, v245, v117
	v_add_f32_e32 v246, v246, v118
	v_add_f32_e32 v247, v247, v119
	ds_bpermute_b32 v248, v237, v240
	ds_bpermute_b32 v249, v237, v241
	ds_bpermute_b32 v250, v237, v242
	ds_bpermute_b32 v251, v237, v243
	ds_bpermute_b32 v116, v237, v244
	ds_bpermute_b32 v117, v237, v245
	ds_bpermute_b32 v118, v237, v246
	ds_bpermute_b32 v119, v237, v247
	s_waitcnt lgkmcnt(0)
	s_and_saveexec_b64 s[0:1], s[2:3]
	v_add_f32_e32 v240, v240, v248
	ds_write_b32 v234, v240
	v_add_f32_e32 v241, v241, v249
	ds_write_b32 v234, v241 offset:256
	v_add_f32_e32 v242, v242, v250
	ds_write_b32 v234, v242 offset:512
	v_add_f32_e32 v243, v243, v251
	ds_write_b32 v234, v243 offset:768
	v_add_f32_e32 v244, v244, v116
	ds_write_b32 v234, v244 offset:2048
	v_add_f32_e32 v245, v245, v117
	ds_write_b32 v234, v245 offset:2304
	v_add_f32_e32 v246, v246, v118
	ds_write_b32 v234, v246 offset:2560
	v_add_f32_e32 v247, v247, v119
	ds_write_b32 v234, v247 offset:2816
	s_or_b64 exec, exec, s[0:1]
	v_add_u32_e32 v114, s21, v213
	s_waitcnt lgkmcnt(0)
	s_barrier
	v_ashrrev_i32_e32 v115, 31, v114
	s_waitcnt lgkmcnt(0)
	v_lshlrev_b64 v[112:113], 5, v[114:115]
	v_lshl_add_u64 v[112:113], s[76:77], 0, v[112:113]
	v_add_u32_e32 v238, 0x20400, v235
	s_and_saveexec_b64 s[0:1], s[4:5]
	s_cbranch_execz .LBB0_620
	ds_read_b128 v[116:119], v238
	s_ashr_i32 s19, s18, 31
	s_waitcnt lgkmcnt(0)
	v_mov_b32_e32 v124, v117
	v_mov_b32_e32 v125, v118
	v_mov_b32_e32 v117, v119
	v_pk_add_f32 v[116:117], v[124:125], v[116:117]
	v_lshl_add_u64 v[118:119], s[18:19], 3, v[112:113]
	v_pk_add_f32 v[116:117], v[116:117], v[116:117] op_sel:[0,1] op_sel_hi:[1,0]
	s_nop 0
	v_mov_b32_e32 v117, s84
	s_waitcnt vmcnt(0)
	flat_store_dwordx2 v[118:119], v[116:117] sc1
